# LN2 forget-gate section: 16 wave reductions batched, lane-parallel log-sigmoid, one 16-lane store (on top of FFN-in epilogue rewrite)
# speedup vs baseline: 1.0860x; 1.0204x over previous
.LBB0_1144:
	v_lshl_add_u64 v[82:83], v[54:55], 0, s[8:9]
	v_lshl_add_u64 v[84:85], v[82:83], 0, s[46:47]
	v_add_co_u32_e32 v82, vcc, s82, v82
	s_add_u32 s8, s8, 0x204000
	s_nop 0
	v_addc_co_u32_e32 v83, vcc, 0, v83, vcc
	global_load_dwordx4 v[92:95], v[82:83], off
	global_load_dwordx4 v[96:99], v[84:85], off offset:48
	global_load_dwordx4 v[100:103], v[84:85], off offset:32
	global_load_dwordx4 v[104:107], v[84:85], off offset:16
	s_nop 0
	global_load_dwordx2 v[82:83], v[62:63], off offset:-4
	global_load_dwordx2 v[84:85], v[64:65], off offset:-4
	s_addc_u32 s9, s9, 0
	v_lshl_add_u64 v[64:65], v[64:65], 0, s[74:75]
	v_lshl_add_u64 v[62:63], v[62:63], 0, s[74:75]
	s_cmp_eq_u32 s8, 0x810000
	s_waitcnt vmcnt(1)
	v_lshlrev_b32_e32 v77, 16, v82
	s_waitcnt vmcnt(0)
	v_lshlrev_b32_e32 v61, 16, v84
	v_add_f32_e32 v108, v77, v61
	v_pk_fma_f32 v[80:81], v[92:93], v[108:109], v[80:81] op_sel_hi:[1,0,1]
	v_pk_fma_f32 v[74:75], v[94:95], v[108:109], v[74:75] op_sel_hi:[1,0,1]
	v_pk_fma_f32 v[104:105], v[104:105], v[108:109], v[72:73] op_sel_hi:[1,0,1]
	v_pk_fma_f32 v[106:107], v[106:107], v[108:109], v[70:71] op_sel_hi:[1,0,1]
	v_pk_fma_f32 v[100:101], v[100:101], v[108:109], v[68:69] op_sel_hi:[1,0,1]
	v_pk_fma_f32 v[102:103], v[102:103], v[108:109], v[66:67] op_sel_hi:[1,0,1]
	v_pk_fma_f32 v[96:97], v[96:97], v[108:109], v[2:3] op_sel_hi:[1,0,1]
	v_pk_fma_f32 v[98:99], v[98:99], v[108:109], v[0:1] op_sel_hi:[1,0,1]
	v_add_u32_e32 v0, -2, v53
	v_mov_b64_e32 v[108:109], s[16:17]
	v_mad_u64_u32 v[0:1], s[10:11], v0, s53, v[108:109]
	v_lshl_add_u64 v[92:93], v[0:1], 0, s[46:47]
	v_add_co_u32_e32 v0, vcc, s82, v0
	v_and_b32_e32 v61, 0xffff0000, v84
	s_nop 0
	v_addc_co_u32_e32 v1, vcc, 0, v1, vcc
	global_load_dwordx4 v[0:3], v[0:1], off
	s_nop 0
	global_load_dwordx4 v[66:69], v[92:93], off offset:48
	global_load_dwordx4 v[70:73], v[92:93], off offset:32
	s_nop 0
	global_load_dwordx4 v[92:95], v[92:93], off offset:16
	v_and_b32_e32 v77, 0xffff0000, v82
	v_add_f32_e32 v82, v77, v61
	v_lshlrev_b32_e32 v61, 16, v85
	v_lshlrev_b32_e32 v77, 16, v83
	s_waitcnt vmcnt(3)
	v_pk_fma_f32 v[80:81], v[0:1], v[82:83], v[80:81] op_sel_hi:[1,0,1]
	v_add_u32_e32 v0, -1, v53
	v_mad_u64_u32 v[0:1], s[10:11], v0, s53, v[108:109]
	s_waitcnt vmcnt(0)
	v_pk_fma_f32 v[104:105], v[92:93], v[82:83], v[104:105] op_sel_hi:[1,0,1]
	v_lshl_add_u64 v[92:93], v[0:1], 0, s[46:47]
	v_add_co_u32_e32 v0, vcc, s82, v0
	v_pk_fma_f32 v[74:75], v[2:3], v[82:83], v[74:75] op_sel_hi:[1,0,1]
	s_nop 0
	v_addc_co_u32_e32 v1, vcc, 0, v1, vcc
	v_pk_fma_f32 v[106:107], v[94:95], v[82:83], v[106:107] op_sel_hi:[1,0,1]
	v_pk_fma_f32 v[100:101], v[70:71], v[82:83], v[100:101] op_sel_hi:[1,0,1]
	v_pk_fma_f32 v[102:103], v[72:73], v[82:83], v[102:103] op_sel_hi:[1,0,1]
	v_pk_fma_f32 v[96:97], v[66:67], v[82:83], v[96:97] op_sel_hi:[1,0,1]
	v_pk_fma_f32 v[98:99], v[68:69], v[82:83], v[98:99] op_sel_hi:[1,0,1]
	global_load_dwordx4 v[0:3], v[0:1], off
	s_nop 0
	global_load_dwordx4 v[66:69], v[92:93], off offset:48
	global_load_dwordx4 v[70:73], v[92:93], off offset:32
	s_nop 0
	global_load_dwordx4 v[92:95], v[92:93], off offset:16
	v_add_f32_e32 v82, v77, v61
	v_and_b32_e32 v61, 0xffff0000, v85
	s_waitcnt vmcnt(3)
	v_pk_fma_f32 v[80:81], v[0:1], v[82:83], v[80:81] op_sel_hi:[1,0,1]
	v_mad_u64_u32 v[0:1], s[10:11], v53, s53, v[108:109]
	s_waitcnt vmcnt(2)
	v_pk_fma_f32 v[110:111], v[66:67], v[82:83], v[96:97] op_sel_hi:[1,0,1]
	v_lshl_add_u64 v[66:67], v[0:1], 0, s[46:47]
	v_add_co_u32_e32 v0, vcc, s82, v0
	v_pk_fma_f32 v[74:75], v[2:3], v[82:83], v[74:75] op_sel_hi:[1,0,1]
	s_nop 0
	v_addc_co_u32_e32 v1, vcc, 0, v1, vcc
	s_waitcnt vmcnt(0)
	v_pk_fma_f32 v[104:105], v[92:93], v[82:83], v[104:105] op_sel_hi:[1,0,1]
	v_pk_fma_f32 v[106:107], v[94:95], v[82:83], v[106:107] op_sel_hi:[1,0,1]
	v_pk_fma_f32 v[112:113], v[68:69], v[82:83], v[98:99] op_sel_hi:[1,0,1]
	global_load_dwordx4 v[0:3], v[0:1], off
	s_nop 0
	global_load_dwordx4 v[92:95], v[66:67], off offset:48
	global_load_dwordx4 v[96:99], v[66:67], off offset:32
	s_nop 0
	global_load_dwordx4 v[66:69], v[66:67], off offset:16
	v_pk_fma_f32 v[100:101], v[70:71], v[82:83], v[100:101] op_sel_hi:[1,0,1]
	v_and_b32_e32 v70, 0xffff0000, v83
	v_pk_fma_f32 v[102:103], v[72:73], v[82:83], v[102:103] op_sel_hi:[1,0,1]
	v_add_f32_e32 v82, v70, v61
	v_add_u32_e32 v53, 0x100, v53
	s_waitcnt vmcnt(3)
	v_pk_fma_f32 v[80:81], v[0:1], v[82:83], v[80:81] op_sel_hi:[1,0,1]
	v_pk_fma_f32 v[74:75], v[2:3], v[82:83], v[74:75] op_sel_hi:[1,0,1]
	s_waitcnt vmcnt(2)
	v_pk_fma_f32 v[2:3], v[92:93], v[82:83], v[110:111] op_sel_hi:[1,0,1]
	s_waitcnt vmcnt(0)
	v_pk_fma_f32 v[72:73], v[66:67], v[82:83], v[104:105] op_sel_hi:[1,0,1]
	v_pk_fma_f32 v[70:71], v[68:69], v[82:83], v[106:107] op_sel_hi:[1,0,1]
	v_pk_fma_f32 v[68:69], v[96:97], v[82:83], v[100:101] op_sel_hi:[1,0,1]
	v_pk_fma_f32 v[66:67], v[98:99], v[82:83], v[102:103] op_sel_hi:[1,0,1]
	v_pk_fma_f32 v[0:1], v[94:95], v[82:83], v[112:113] op_sel_hi:[1,0,1]
	s_cbranch_scc0 .LBB0_1144
	s_mov_b64 s[8:9], exec
	v_and_b32_e32 v109, 60, v28
	global_load_dword v110, v109, s[18:19]
	ds_bpermute_b32 v92, v29, v80
	ds_bpermute_b32 v93, v29, v81
	ds_bpermute_b32 v94, v29, v74
	ds_bpermute_b32 v95, v29, v75
	ds_bpermute_b32 v96, v29, v72
	ds_bpermute_b32 v97, v29, v73
	ds_bpermute_b32 v98, v29, v70
	ds_bpermute_b32 v99, v29, v71
	s_waitcnt lgkmcnt(0)
	ds_bpermute_b32 v100, v29, v68
	ds_bpermute_b32 v101, v29, v69
	ds_bpermute_b32 v102, v29, v66
	ds_bpermute_b32 v103, v29, v67
	ds_bpermute_b32 v104, v29, v2
	ds_bpermute_b32 v105, v29, v3
	ds_bpermute_b32 v106, v29, v0
	ds_bpermute_b32 v107, v29, v1
	v_add_f32_e32 v80, v80, v92
	v_add_f32_e32 v81, v81, v93
	v_add_f32_e32 v74, v74, v94
	v_add_f32_e32 v75, v75, v95
	v_add_f32_e32 v72, v72, v96
	v_add_f32_e32 v73, v73, v97
	v_add_f32_e32 v70, v70, v98
	v_add_f32_e32 v71, v71, v99
	s_waitcnt lgkmcnt(0)
	ds_bpermute_b32 v92, v86, v80
	ds_bpermute_b32 v93, v86, v81
	ds_bpermute_b32 v94, v86, v74
	ds_bpermute_b32 v95, v86, v75
	ds_bpermute_b32 v96, v86, v72
	ds_bpermute_b32 v97, v86, v73
	ds_bpermute_b32 v98, v86, v70
	ds_bpermute_b32 v99, v86, v71
	v_add_f32_e32 v68, v68, v100
	v_add_f32_e32 v69, v69, v101
	v_add_f32_e32 v66, v66, v102
	v_add_f32_e32 v67, v67, v103
	v_add_f32_e32 v2, v2, v104
	v_add_f32_e32 v3, v3, v105
	v_add_f32_e32 v0, v0, v106
	v_add_f32_e32 v1, v1, v107
	s_waitcnt lgkmcnt(0)
	ds_bpermute_b32 v100, v86, v68
	ds_bpermute_b32 v101, v86, v69
	ds_bpermute_b32 v102, v86, v66
	ds_bpermute_b32 v103, v86, v67
	ds_bpermute_b32 v104, v86, v2
	ds_bpermute_b32 v105, v86, v3
	ds_bpermute_b32 v106, v86, v0
	ds_bpermute_b32 v107, v86, v1
	v_add_f32_e32 v80, v80, v92
	v_add_f32_e32 v81, v81, v93
	v_add_f32_e32 v74, v74, v94
	v_add_f32_e32 v75, v75, v95
	v_add_f32_e32 v72, v72, v96
	v_add_f32_e32 v73, v73, v97
	v_add_f32_e32 v70, v70, v98
	v_add_f32_e32 v71, v71, v99
	s_waitcnt lgkmcnt(0)
	ds_bpermute_b32 v92, v87, v80
	ds_bpermute_b32 v93, v87, v81
	ds_bpermute_b32 v94, v87, v74
	ds_bpermute_b32 v95, v87, v75
	ds_bpermute_b32 v96, v87, v72
	ds_bpermute_b32 v97, v87, v73
	ds_bpermute_b32 v98, v87, v70
	ds_bpermute_b32 v99, v87, v71
	v_add_f32_e32 v68, v68, v100
	v_add_f32_e32 v69, v69, v101
	v_add_f32_e32 v66, v66, v102
	v_add_f32_e32 v67, v67, v103
	v_add_f32_e32 v2, v2, v104
	v_add_f32_e32 v3, v3, v105
	v_add_f32_e32 v0, v0, v106
	v_add_f32_e32 v1, v1, v107
	s_waitcnt lgkmcnt(0)
	ds_bpermute_b32 v100, v87, v68
	ds_bpermute_b32 v101, v87, v69
	ds_bpermute_b32 v102, v87, v66
	ds_bpermute_b32 v103, v87, v67
	ds_bpermute_b32 v104, v87, v2
	ds_bpermute_b32 v105, v87, v3
	ds_bpermute_b32 v106, v87, v0
	ds_bpermute_b32 v107, v87, v1
	v_add_f32_e32 v80, v80, v92
	v_add_f32_e32 v81, v81, v93
	v_add_f32_e32 v74, v74, v94
	v_add_f32_e32 v75, v75, v95
	v_add_f32_e32 v72, v72, v96
	v_add_f32_e32 v73, v73, v97
	v_add_f32_e32 v70, v70, v98
	v_add_f32_e32 v71, v71, v99
	s_waitcnt lgkmcnt(0)
	ds_bpermute_b32 v92, v88, v80
	ds_bpermute_b32 v93, v88, v81
	ds_bpermute_b32 v94, v88, v74
	ds_bpermute_b32 v95, v88, v75
	ds_bpermute_b32 v96, v88, v72
	ds_bpermute_b32 v97, v88, v73
	ds_bpermute_b32 v98, v88, v70
	ds_bpermute_b32 v99, v88, v71
	v_add_f32_e32 v68, v68, v100
	v_add_f32_e32 v69, v69, v101
	v_add_f32_e32 v66, v66, v102
	v_add_f32_e32 v67, v67, v103
	v_add_f32_e32 v2, v2, v104
	v_add_f32_e32 v3, v3, v105
	v_add_f32_e32 v0, v0, v106
	v_add_f32_e32 v1, v1, v107
	s_waitcnt lgkmcnt(0)
	ds_bpermute_b32 v100, v88, v68
	ds_bpermute_b32 v101, v88, v69
	ds_bpermute_b32 v102, v88, v66
	ds_bpermute_b32 v103, v88, v67
	ds_bpermute_b32 v104, v88, v2
	ds_bpermute_b32 v105, v88, v3
	ds_bpermute_b32 v106, v88, v0
	ds_bpermute_b32 v107, v88, v1
	v_add_f32_e32 v80, v80, v92
	v_add_f32_e32 v81, v81, v93
	v_add_f32_e32 v74, v74, v94
	v_add_f32_e32 v75, v75, v95
	v_add_f32_e32 v72, v72, v96
	v_add_f32_e32 v73, v73, v97
	v_add_f32_e32 v70, v70, v98
	v_add_f32_e32 v71, v71, v99
	s_waitcnt lgkmcnt(0)
	ds_bpermute_b32 v92, v89, v80
	ds_bpermute_b32 v93, v89, v81
	ds_bpermute_b32 v94, v89, v74
	ds_bpermute_b32 v95, v89, v75
	ds_bpermute_b32 v96, v89, v72
	ds_bpermute_b32 v97, v89, v73
	ds_bpermute_b32 v98, v89, v70
	ds_bpermute_b32 v99, v89, v71
	v_add_f32_e32 v68, v68, v100
	v_add_f32_e32 v69, v69, v101
	v_add_f32_e32 v66, v66, v102
	v_add_f32_e32 v67, v67, v103
	v_add_f32_e32 v2, v2, v104
	v_add_f32_e32 v3, v3, v105
	v_add_f32_e32 v0, v0, v106
	v_add_f32_e32 v1, v1, v107
	s_waitcnt lgkmcnt(0)
	ds_bpermute_b32 v100, v89, v68
	ds_bpermute_b32 v101, v89, v69
	ds_bpermute_b32 v102, v89, v66
	ds_bpermute_b32 v103, v89, v67
	ds_bpermute_b32 v104, v89, v2
	ds_bpermute_b32 v105, v89, v3
	ds_bpermute_b32 v106, v89, v0
	ds_bpermute_b32 v107, v89, v1
	v_add_f32_e32 v80, v80, v92
	v_add_f32_e32 v81, v81, v93
	v_add_f32_e32 v74, v74, v94
	v_add_f32_e32 v75, v75, v95
	v_add_f32_e32 v72, v72, v96
	v_add_f32_e32 v73, v73, v97
	v_add_f32_e32 v70, v70, v98
	v_add_f32_e32 v71, v71, v99
	s_waitcnt lgkmcnt(0)
	ds_bpermute_b32 v92, v90, v80
	ds_bpermute_b32 v93, v90, v81
	ds_bpermute_b32 v94, v90, v74
	ds_bpermute_b32 v95, v90, v75
	ds_bpermute_b32 v96, v90, v72
	ds_bpermute_b32 v97, v90, v73
	ds_bpermute_b32 v98, v90, v70
	ds_bpermute_b32 v99, v90, v71
	v_add_f32_e32 v68, v68, v100
	v_add_f32_e32 v69, v69, v101
	v_add_f32_e32 v66, v66, v102
	v_add_f32_e32 v67, v67, v103
	v_add_f32_e32 v2, v2, v104
	v_add_f32_e32 v3, v3, v105
	v_add_f32_e32 v0, v0, v106
	v_add_f32_e32 v1, v1, v107
	s_waitcnt lgkmcnt(0)
	ds_bpermute_b32 v100, v90, v68
	ds_bpermute_b32 v101, v90, v69
	ds_bpermute_b32 v102, v90, v66
	ds_bpermute_b32 v103, v90, v67
	ds_bpermute_b32 v104, v90, v2
	ds_bpermute_b32 v105, v90, v3
	ds_bpermute_b32 v106, v90, v0
	ds_bpermute_b32 v107, v90, v1
	v_add_f32_e32 v80, v80, v92
	v_add_f32_e32 v81, v81, v93
	v_add_f32_e32 v74, v74, v94
	v_add_f32_e32 v75, v75, v95
	v_add_f32_e32 v72, v72, v96
	v_add_f32_e32 v73, v73, v97
	v_add_f32_e32 v70, v70, v98
	v_add_f32_e32 v71, v71, v99
	s_waitcnt lgkmcnt(0)
	v_add_f32_e32 v68, v68, v100
	v_add_f32_e32 v69, v69, v101
	v_add_f32_e32 v66, v66, v102
	v_add_f32_e32 v67, v67, v103
	v_add_f32_e32 v2, v2, v104
	v_add_f32_e32 v3, v3, v105
	v_add_f32_e32 v0, v0, v106
	v_add_f32_e32 v1, v1, v107
	v_mov_b32_e32 v108, v80
	s_mov_b64 vcc, 2
	s_mov_b64 s[10:11], 4
	v_cndmask_b32_e32 v108, v108, v81, vcc
	s_mov_b64 vcc, 8
	v_cndmask_b32_e64 v108, v108, v74, s[10:11]
	s_mov_b64 s[10:11], 16
	v_cndmask_b32_e32 v108, v108, v75, vcc
	s_mov_b64 vcc, 32
	v_cndmask_b32_e64 v108, v108, v72, s[10:11]
	s_mov_b64 s[10:11], 64
	v_cndmask_b32_e32 v108, v108, v73, vcc
	s_mov_b64 vcc, 128
	v_cndmask_b32_e64 v108, v108, v70, s[10:11]
	s_mov_b64 s[10:11], 256
	v_cndmask_b32_e32 v108, v108, v71, vcc
	s_mov_b64 vcc, 512
	v_cndmask_b32_e64 v108, v108, v68, s[10:11]
	s_mov_b64 s[10:11], 1024
	v_cndmask_b32_e32 v108, v108, v69, vcc
	s_mov_b64 vcc, 2048
	v_cndmask_b32_e64 v108, v108, v66, s[10:11]
	s_mov_b64 s[10:11], 4096
	v_cndmask_b32_e32 v108, v108, v67, vcc
	s_mov_b64 vcc, 8192
	v_cndmask_b32_e64 v108, v108, v2, s[10:11]
	s_mov_b64 s[10:11], 16384
	v_cndmask_b32_e32 v108, v108, v3, vcc
	s_mov_b64 vcc, 32768
	v_cndmask_b32_e64 v108, v108, v0, s[10:11]
	v_cndmask_b32_e32 v108, v108, v1, vcc
	s_waitcnt vmcnt(0)
	v_add_f32_e32 v108, v110, v108
	v_mul_f32_e64 v111, |v108|, s97
	v_exp_f32_e32 v111, v111
	s_nop 0
	v_add_f32_e32 v112, 1.0, v111
	v_log_f32_e32 v112, v112
	v_fmamk_f32 v113, v111, 0xbe800000, v194
	v_fma_f32 v113, -v111, v113, 0.5
	v_fma_f32 v113, -v111, v113, 1.0
	v_mul_f32_e32 v113, v111, v113
	v_mul_f32_e32 v61, 0x3f317217, v112
	v_fma_f32 v61, v112, s76, -v61
	v_fmac_f32_e32 v61, 0x3377d1cf, v112
	v_fmac_f32_e32 v61, 0x3f317217, v112
	v_cmp_ngt_f32_e32 vcc, s90, v111
	v_ashrrev_i32_e32 v79, 31, v78
	v_lshl_add_u64 v[62:63], v[78:79], 2, s[34:35]
	v_cndmask_b32_e32 v61, v113, v61, vcc
	v_mul_hi_i32_i24_e32 v65, 0x20400, v76
	v_mul_i32_i24_e32 v64, 0x20400, v76
	v_max_f32_e32 v108, v108, v108
	v_min_f32_e32 v108, 0, v108
	v_lshl_add_u64 v[62:63], v[62:63], 0, v[64:65]
	v_mul_u32_u24_e32 v64, 0x810, v109
	v_mov_b32_e32 v65, 0
	v_sub_f32_e32 v108, v108, v61
	v_lshl_add_u64 v[62:63], v[62:63], 0, v[64:65]
	s_mov_b64 exec, 0xffff
	global_store_dword v[62:63], v108, off
	s_mov_b64 exec, s[8:9]
	s_branch .LBB0_1110
